# P0 bias tables: maxima computed once per wave cooperatively (DPP max-reduce) instead of serial dependent loads; on top of v27
# speedup vs baseline: 1.0132x; 1.0132x over previous
; __global__ void __launch_bounds__(512, 2) hybrid_fwd(Params p) {
;     ...
;         for (int i = gtid; i < 2 * 12 * 260; i += NT) {
;             const int lh = i / 260, o = i - lh * 260, li2 = lh / 12, h = lh - li2 * 12;
;             float mg = 0.f, mb = 0.f;
;             for (int d = 0; d < 128; ++d) mg = fmaxf(mg, fabsf(p.q_gain[li2 * 128 + d] * p.k_gain[li2 * 128 + d]));
;             for (int q = 0; q < 32 * 12; ++q) mb = fmaxf(mb, fabsf(p.rel_bias[q]));
;             const float B2 = (11.313708498984761f * mg * 1.01f + mb + 0.1f) * LOG2E;
;             float v = 0.f;
;             if (o <= 256) v = p.rel_bias[t5_bucket(o - 128) * 12 + h] * LOG2E - B2;
.LBB0_97:
	s_or_b64 exec, exec, s[4:5]
	s_movk_i32 s0, 0x1860
	v_cmp_gt_i32_e32 vcc, s0, v2
	s_waitcnt lgkmcnt(0)
	s_barrier
	s_and_saveexec_b64 s[6:7], vcc
	s_cbranch_execz .LBB0_118
	s_mov_b64 s[18:19], 0
	s_mov_b32 s0, 0xa80a80a9
	v_mov_b32_e32 v10, 0
	s_mov_b32 s1, 0x7e07e07f
	s_movk_i32 s2, 0xfefc
	s_movk_i32 s14, 0x100
	s_movk_i32 s15, 0x101
	s_movk_i32 s17, 0x80
	s_movk_i32 s34, 0x5a
	s_mov_b32 s35, 0x3fb8aa3b
	s_movk_i32 s36, 0x185f
	v_mov_b32_e32 v4, v2
	s_mov_b64 s[48:49], exec
	s_mov_b64 exec, -1
	v_and_b32_e32 v142, 63, v254
	v_lshlrev_b32_e32 v142, 2, v142
	global_load_dword v143, v142, s[28:29]
	global_load_dword v147, v142, s[30:31]
	global_load_dword v144, v142, s[28:29] offset:256
	global_load_dword v148, v142, s[30:31] offset:256
	global_load_dword v145, v142, s[28:29] offset:512
	global_load_dword v149, v142, s[30:31] offset:512
	global_load_dword v146, v142, s[28:29] offset:768
	global_load_dword v150, v142, s[30:31] offset:768
	global_load_dword v151, v142, s[22:23]
	global_load_dword v152, v142, s[22:23] offset:256
	global_load_dword v153, v142, s[22:23] offset:512
	global_load_dword v154, v142, s[22:23] offset:768
	global_load_dword v155, v142, s[22:23] offset:1024
	global_load_dword v156, v142, s[22:23] offset:1280
	s_waitcnt vmcnt(0)
	v_mul_f32_e32 v143, v143, v147
	v_mul_f32_e32 v144, v144, v148
	v_mul_f32_e32 v145, v145, v149
	v_mul_f32_e32 v146, v146, v150
	v_max_f32_e64 v143, |v143|, |v144|
	v_max_f32_e64 v144, |v145|, |v146|
	v_max_f32_e64 v145, |v151|, |v152|
	v_max_f32_e64 v146, |v153|, |v154|
	v_max_f32_e64 v147, |v155|, |v156|
	v_max_f32_e32 v145, v145, v146
	v_max_f32_e32 v145, v145, v147
	v_max_f32_dpp v143, v143, v143 quad_perm:[1,0,3,2] row_mask:0xf bank_mask:0xf
	v_max_f32_dpp v144, v144, v144 quad_perm:[1,0,3,2] row_mask:0xf bank_mask:0xf
	v_max_f32_dpp v145, v145, v145 quad_perm:[1,0,3,2] row_mask:0xf bank_mask:0xf
	s_nop 0
	v_max_f32_dpp v143, v143, v143 quad_perm:[2,3,0,1] row_mask:0xf bank_mask:0xf
	v_max_f32_dpp v144, v144, v144 quad_perm:[2,3,0,1] row_mask:0xf bank_mask:0xf
	v_max_f32_dpp v145, v145, v145 quad_perm:[2,3,0,1] row_mask:0xf bank_mask:0xf
	s_nop 0
	v_max_f32_dpp v143, v143, v143 row_half_mirror row_mask:0xf bank_mask:0xf
	v_max_f32_dpp v144, v144, v144 row_half_mirror row_mask:0xf bank_mask:0xf
	v_max_f32_dpp v145, v145, v145 row_half_mirror row_mask:0xf bank_mask:0xf
	s_nop 0
	v_max_f32_dpp v143, v143, v143 row_mirror row_mask:0xf bank_mask:0xf
	v_max_f32_dpp v144, v144, v144 row_mirror row_mask:0xf bank_mask:0xf
	v_max_f32_dpp v145, v145, v145 row_mirror row_mask:0xf bank_mask:0xf
	s_nop 0
	s_nop 1
	v_readlane_b32 s50, v143, 0
	v_readlane_b32 s53, v143, 16
	v_readlane_b32 s54, v143, 32
	v_readlane_b32 s55, v143, 48
	s_nop 1
	s_max_u32 s50, s50, s53
	s_max_u32 s54, s54, s55
	s_max_u32 s50, s50, s54
	v_readlane_b32 s51, v144, 0
	v_readlane_b32 s53, v144, 16
	v_readlane_b32 s54, v144, 32
	v_readlane_b32 s55, v144, 48
	s_nop 1
	s_max_u32 s51, s51, s53
	s_max_u32 s54, s54, s55
	s_max_u32 s51, s51, s54
	v_readlane_b32 s52, v145, 0
	v_readlane_b32 s53, v145, 16
	v_readlane_b32 s54, v145, 32
	v_readlane_b32 s55, v145, 48
	s_nop 1
	s_max_u32 s52, s52, s53
	s_max_u32 s54, s54, s55
	s_max_u32 s52, s52, s54
	s_mov_b64 exec, s[48:49]
	s_branch .LBB0_100

; __global__ void __launch_bounds__(512, 2) hybrid_fwd(Params p) {
;     ...
;             const int lh = i / 260, o = i - lh * 260, li2 = lh / 12, h = lh - li2 * 12;
;             float mg = 0.f, mb = 0.f;
;             for (int d = 0; d < 128; ++d) mg = fmaxf(mg, fabsf(p.q_gain[li2 * 128 + d] * p.k_gain[li2 * 128 + d]));
;             for (int q = 0; q < 32 * 12; ++q) mb = fmaxf(mb, fabsf(p.rel_bias[q]));
;             const float B2 = (11.313708498984761f * mg * 1.01f + mb + 0.1f) * LOG2E;
.LBB0_100:
	v_mul_hi_i32 v5, v4, s0
	v_add_u32_e32 v5, v5, v4
	v_lshrrev_b32_e32 v6, 31, v5
	v_ashrrev_i32_e32 v5, 11, v5
	v_add_u32_e32 v5, v5, v6
	v_lshlrev_b32_e32 v6, 7, v5
	v_ashrrev_i32_e32 v7, 31, v6
	v_lshlrev_b64 v[8:9], 2, v[6:7]
	v_lshl_add_u64 v[6:7], s[30:31], 0, v[8:9]
	v_lshl_add_u64 v[8:9], s[28:29], 0, v[8:9]
	v_cmp_ne_u32_e32 vcc, 0, v5
	v_mov_b32_e32 v11, s50
	v_mov_b32_e32 v12, s51
	s_nop 1
	v_cndmask_b32_e32 v11, v11, v12, vcc
	v_mov_b32_e32 v12, s52
